# GLA-output item: gain and first gate-residual loads issued before the cross-lane sum-of-squares reduction instead of after it
# baseline (speedup 1.0000x reference)
; DI f32x4 mfma16(bf16x8 a, bf16x8 b, f32x4 c) { return __builtin_amdgcn_mfma_f32_16x16x32_bf16(a, b, c, 0, 0, 0); }
; DI void go_compute(int l, const unsigned char* base, const bf16x8 (&qq)[4], int item, int tb, int lane) {
;     unsigned char* R = WSP() + WS_R;
;     const bf16* GR = (const bf16*)(R + R_GR); bf16* MIX = (bf16*)(R + R_MIX);
;     const int ck = item & 63, bh = item >> 6, h = bh & 3, b = bh >> 2, c = lane & 15, g = lane >> 4;
;     const size_t tok0 = (size_t)b * SEQ + ck * 64;
;     const bf16x8 qf0 = qq[0], qf1 = qq[1], qb0 = qq[2], qb1 = qq[3];
;     f32x4 at[4];
; #pragma unroll
;     for (int sb = 0; sb < 4; ++sb) {
;         const unsigned char* kf = base + GO_KF + (16 * sb + c) * 144 + g * 16; const unsigned char* kb = base + GO_KB + (16 * sb + c) * 144 + g * 16;
;         f32x4 f = {0.f, 0.f, 0.f, 0.f}, bk = {0.f, 0.f, 0.f, 0.f};
;         f = mfma16(*(const bf16x8*)kf, qf0, f); f = mfma16(*(const bf16x8*)(kf + 64), qf1, f);
;         bk = mfma16(*(const bf16x8*)kb, qb0, bk); bk = mfma16(*(const bf16x8*)(kb + 64), qb1, bk);
; #pragma unroll
;         for (int i = 0; i < 4; ++i) at[sb][i] = (16 * sb + 4 * g + i <= 16 * tb + c) ? f[i] : bk[i];
;     }
;     const bf16x8 p0 = pack8(at[0], at[1]), p1 = pack8(at[2], at[3]);
;     f32x4 o[8]; float ss = 0.f;
; #pragma unroll
;     for (int eb = 0; eb < 8; ++eb) {
;         const unsigned char* vp = base + GO_VT + (g >> 1) * 2048 + (16 * eb + c) * 16 + (g & 1) * 8;
;         const u32x2 v0 = *(const u32x2*)vp, v1 = *(const u32x2*)(vp + 4096), v2 = *(const u32x2*)(vp + 8192), v3 = *(const u32x2*)(vp + 12288);
;         u32x4 a0; a0.x = v0.x; a0.y = v0.y; a0.z = v1.x; a0.w = v1.y; u32x4 a1; a1.x = v2.x; a1.y = v2.y; a1.z = v3.x; a1.w = v3.y;
;         const unsigned char* sfp = base + GO_SF + (16 * eb + c) * 144 + g * 16; const unsigned char* sbp = base + GO_SB + (16 * eb + c) * 144 + g * 16;
;         f32x4 acc = {0.f, 0.f, 0.f, 0.f};
;         acc = mfma16(__builtin_bit_cast(bf16x8, a0), p0, acc); acc = mfma16(__builtin_bit_cast(bf16x8, a1), p1, acc);
;         acc = mfma16(*(const bf16x8*)sfp, qf0, acc); acc = mfma16(*(const bf16x8*)(sfp + 64), qf1, acc);
;         acc = mfma16(*(const bf16x8*)sbp, qb0, acc); acc = mfma16(*(const bf16x8*)(sbp + 64), qb1, acc);
;         o[eb] = acc; ss += (acc[0] * acc[0] + acc[1] * acc[1]) + (acc[2] * acc[2] + acc[3] * acc[3]);
;     }
.LBB0_873:
	v_readlane_b32 s8, v244, 9
	s_add_i32 s8, s8, s31
	v_readlane_b32 s12, v246, 63
	s_or_b32 s8, s8, s12
	s_movk_i32 s12, 0xa8
	ds_read_b128 v[98:101], v161
	ds_read_b128 v[102:105], v161 offset:64
	s_ashr_i32 s13, s12, 31
	s_add_u32 s12, s0, s12
	s_addc_u32 s13, s1, s13
	s_load_dwordx2 s[40:41], s[12:13], 0x0
	s_waitcnt lgkmcnt(0)
	v_mfma_f32_16x16x32_bf16 v[98:101], v[98:101], v[94:97], 0
	ds_read_b128 v[106:109], v161 offset:9280
	s_ashr_i32 s12, s8, 8
	s_ashr_i32 s13, s12, 31
	v_mfma_f32_16x16x32_bf16 v[98:101], v[102:105], v[90:93], v[98:101]
	ds_read_b128 v[102:105], v161 offset:9216
	s_and_b32 s8, s30, 0xfc0
	s_lshl_b64 s[12:13], s[12:13], 12
	s_or_b32 s8, s12, s8
	s_movk_i32 s12, 0x68
	s_waitcnt lgkmcnt(0)
	v_mfma_f32_16x16x32_bf16 v[102:105], v[102:105], v[86:89], 0
	v_mfma_f32_16x16x32_bf16 v[102:105], v[106:109], v[82:85], v[102:105]
	ds_read_b128 v[106:109], v161 offset:11584
	s_nop 6
	v_cndmask_b32_e64 v0, v98, v102, s[42:43]
	v_cndmask_b32_e64 v110, v103, v99, s[44:45]
	v_cndmask_b32_e64 v111, v100, v104, s[46:47]
	v_cndmask_b32_e64 v112, v101, v105, s[48:49]
	ds_read_b128 v[98:101], v161 offset:2304
	ds_read_b128 v[102:105], v161 offset:2368
	s_waitcnt lgkmcnt(1)
	v_mfma_f32_16x16x32_bf16 v[98:101], v[98:101], v[94:97], 0
	v_cvt_pk_bf16_f32 v114, v0, v110
	v_add_u32_e32 v0, v145, v147
	v_cvt_pk_bf16_f32 v115, v111, v112
	s_waitcnt lgkmcnt(0)
	v_mfma_f32_16x16x32_bf16 v[98:101], v[102:105], v[90:93], v[98:101]
	ds_read_b128 v[102:105], v161 offset:11520
	s_waitcnt lgkmcnt(0)
	v_mfma_f32_16x16x32_bf16 v[102:105], v[102:105], v[86:89], 0
	v_mfma_f32_16x16x32_bf16 v[102:105], v[106:109], v[82:85], v[102:105]
	ds_read_b128 v[106:109], v161 offset:13888
	s_nop 6
	v_cndmask_b32_e64 v113, v98, v102, s[50:51]
	v_cndmask_b32_e64 v116, v99, v103, s[52:53]
	v_cndmask_b32_e64 v117, v100, v104, s[54:55]
	v_cndmask_b32_e64 v118, v101, v105, s[56:57]
	ds_read_b128 v[98:101], v161 offset:4608
	ds_read_b128 v[102:105], v161 offset:4672
	s_waitcnt lgkmcnt(1)
	v_mfma_f32_16x16x32_bf16 v[98:101], v[98:101], v[94:97], 0
	v_cvt_pk_bf16_f32 v117, v117, v118
	v_cvt_pk_bf16_f32 v116, v113, v116
	s_waitcnt lgkmcnt(0)
	v_mfma_f32_16x16x32_bf16 v[98:101], v[102:105], v[90:93], v[98:101]
	ds_read_b128 v[102:105], v161 offset:13824
	s_waitcnt lgkmcnt(0)
	v_mfma_f32_16x16x32_bf16 v[102:105], v[102:105], v[86:89], 0
	v_mfma_f32_16x16x32_bf16 v[102:105], v[106:109], v[82:85], v[102:105]
	ds_read_b128 v[106:109], v162 offset:9280
	s_nop 6
	v_cndmask_b32_e64 v119, v98, v102, s[58:59]
	v_cndmask_b32_e64 v120, v99, v103, s[60:61]
	v_cndmask_b32_e64 v121, v100, v104, s[62:63]
	v_cndmask_b32_e64 v122, v101, v105, s[64:65]
	ds_read_b128 v[98:101], v162
	ds_read_b128 v[102:105], v162 offset:64
	s_waitcnt lgkmcnt(1)
	v_mfma_f32_16x16x32_bf16 v[98:101], v[98:101], v[94:97], 0
	v_cvt_pk_bf16_f32 v118, v119, v120
	v_cvt_pk_bf16_f32 v119, v121, v122
	s_waitcnt lgkmcnt(0)
	v_mfma_f32_16x16x32_bf16 v[98:101], v[102:105], v[90:93], v[98:101]
	ds_read_b128 v[102:105], v162 offset:9216
	s_waitcnt lgkmcnt(0)
	v_mfma_f32_16x16x32_bf16 v[102:105], v[102:105], v[86:89], 0
	v_mfma_f32_16x16x32_bf16 v[102:105], v[106:109], v[82:85], v[102:105]
	s_nop 7
	v_cndmask_b32_e64 v98, v98, v102, s[66:67]
	v_cndmask_b32_e64 v99, v99, v103, s[68:69]
	v_cndmask_b32_e64 v100, v100, v104, s[70:71]
	v_cndmask_b32_e64 v101, v101, v105, s[72:73]
	v_cvt_pk_bf16_f32 v120, v98, v99
	v_cvt_pk_bf16_f32 v121, v100, v101
	ds_read2st64_b64 v[208:211], v0 offset0:36 offset1:44
	ds_read2st64_b64 v[212:215], v0 offset0:52 offset1:60
	ds_read_b128 v[216:219], v161 offset:34816
	ds_read_b128 v[220:223], v161 offset:34880
	ds_read_b128 v[224:227], v161 offset:53248
	ds_read_b128 v[228:231], v161 offset:53312
	s_waitcnt lgkmcnt(5)
	v_mfma_f32_16x16x32_bf16 v[98:101], v[208:211], v[114:117], 0
	ds_read2st64_b64 v[232:235], v163 offset0:36 offset1:44
	s_waitcnt lgkmcnt(5)
	v_mfma_f32_16x16x32_bf16 v[98:101], v[212:215], v[118:121], v[98:101]
	ds_read2st64_b64 v[208:211], v163 offset0:52 offset1:60
	s_waitcnt lgkmcnt(5)
	v_mfma_f32_16x16x32_bf16 v[98:101], v[216:219], v[94:97], v[98:101]
	ds_read_b128 v[212:215], v161 offset:37120
	s_waitcnt lgkmcnt(5)
	v_mfma_f32_16x16x32_bf16 v[98:101], v[220:223], v[90:93], v[98:101]
	ds_read_b128 v[216:219], v161 offset:37184
	s_waitcnt lgkmcnt(5)
	v_mfma_f32_16x16x32_bf16 v[98:101], v[224:227], v[86:89], v[98:101]
	ds_read_b128 v[220:223], v161 offset:55552
	s_waitcnt lgkmcnt(5)
	v_mfma_f32_16x16x32_bf16 v[98:101], v[228:231], v[82:85], v[98:101]
	ds_read_b128 v[224:227], v161 offset:55616
	s_waitcnt lgkmcnt(5)
	v_mfma_f32_16x16x32_bf16 v[102:105], v[232:235], v[114:117], 0
	ds_read2st64_b64 v[228:231], v178 offset0:36 offset1:44
	s_waitcnt lgkmcnt(5)
	v_mfma_f32_16x16x32_bf16 v[102:105], v[208:211], v[118:121], v[102:105]
	ds_read2st64_b64 v[232:235], v178 offset0:52 offset1:60
	s_waitcnt lgkmcnt(5)
	v_mfma_f32_16x16x32_bf16 v[102:105], v[212:215], v[94:97], v[102:105]
	ds_read_b128 v[208:211], v161 offset:39424
	v_mul_f32_e32 v240, v99, v99
	v_mul_f32_e32 v241, v101, v101
	v_fmac_f32_e32 v240, v98, v98
	v_fmac_f32_e32 v241, v100, v100
	v_add_f32_e32 v240, v240, v241
	v_mov_b32_e32 v242, v240
	s_waitcnt lgkmcnt(5)
	v_mfma_f32_16x16x32_bf16 v[102:105], v[216:219], v[90:93], v[102:105]
	ds_read_b128 v[212:215], v161 offset:39488
	s_waitcnt lgkmcnt(5)
	v_mfma_f32_16x16x32_bf16 v[102:105], v[220:223], v[86:89], v[102:105]
	ds_read_b128 v[216:219], v161 offset:57856
	s_waitcnt lgkmcnt(5)
	v_mfma_f32_16x16x32_bf16 v[102:105], v[224:227], v[82:85], v[102:105]
	ds_read_b128 v[220:223], v161 offset:57920
	s_waitcnt lgkmcnt(5)
; DI f32x4 mfma16(bf16x8 a, bf16x8 b, f32x4 c) { return __builtin_amdgcn_mfma_f32_16x16x32_bf16(a, b, c, 0, 0, 0); }
; DI void go_compute(int l, const unsigned char* base, const bf16x8 (&qq)[4], int item, int tb, int lane) {
;     ...
; #pragma unroll
;     for (int eb = 0; eb < 8; ++eb) {
;         const unsigned char* vp = base + GO_VT + (g >> 1) * 2048 + (16 * eb + c) * 16 + (g & 1) * 8;
;         const u32x2 v0 = *(const u32x2*)vp, v1 = *(const u32x2*)(vp + 4096), v2 = *(const u32x2*)(vp + 8192), v3 = *(const u32x2*)(vp + 12288);
;         u32x4 a0; a0.x = v0.x; a0.y = v0.y; a0.z = v1.x; a0.w = v1.y; u32x4 a1; a1.x = v2.x; a1.y = v2.y; a1.z = v3.x; a1.w = v3.y;
;         const unsigned char* sfp = base + GO_SF + (16 * eb + c) * 144 + g * 16; const unsigned char* sbp = base + GO_SB + (16 * eb + c) * 144 + g * 16;
;         f32x4 acc = {0.f, 0.f, 0.f, 0.f};
;         acc = mfma16(__builtin_bit_cast(bf16x8, a0), p0, acc); acc = mfma16(__builtin_bit_cast(bf16x8, a1), p1, acc);
;         acc = mfma16(*(const bf16x8*)sfp, qf0, acc); acc = mfma16(*(const bf16x8*)(sfp + 64), qf1, acc);
;         acc = mfma16(*(const bf16x8*)sbp, qb0, acc); acc = mfma16(*(const bf16x8*)(sbp + 64), qb1, acc);
;         o[eb] = acc; ss += (acc[0] * acc[0] + acc[1] * acc[1]) + (acc[2] * acc[2] + acc[3] * acc[3]);
;     }
	v_mfma_f32_16x16x32_bf16 v[106:109], v[228:231], v[114:117], 0
	ds_read2st64_b64 v[224:227], v179 offset0:36 offset1:44
	s_waitcnt lgkmcnt(5)
	v_mfma_f32_16x16x32_bf16 v[106:109], v[232:235], v[118:121], v[106:109]
	ds_read2st64_b64 v[228:231], v179 offset0:52 offset1:60
	s_waitcnt lgkmcnt(5)
	v_mfma_f32_16x16x32_bf16 v[106:109], v[208:211], v[94:97], v[106:109]
	ds_read_b128 v[232:235], v162 offset:34816
	v_mul_f32_e32 v240, v103, v103
	v_mul_f32_e32 v241, v105, v105
	v_fmac_f32_e32 v240, v102, v102
	v_fmac_f32_e32 v241, v104, v104
	v_add_f32_e32 v240, v240, v241
	v_add_f32_e32 v242, v242, v240
	s_waitcnt lgkmcnt(5)
	v_mfma_f32_16x16x32_bf16 v[106:109], v[212:215], v[90:93], v[106:109]
	ds_read_b128 v[208:211], v162 offset:34880
	s_waitcnt lgkmcnt(5)
	v_mfma_f32_16x16x32_bf16 v[106:109], v[216:219], v[86:89], v[106:109]
	ds_read_b128 v[212:215], v162 offset:53248
	s_waitcnt lgkmcnt(5)
	v_mfma_f32_16x16x32_bf16 v[106:109], v[220:223], v[82:85], v[106:109]
	ds_read_b128 v[216:219], v162 offset:53312
	s_waitcnt lgkmcnt(5)
	v_mfma_f32_16x16x32_bf16 v[110:113], v[224:227], v[114:117], 0
	ds_read2st64_b64 v[220:223], v180 offset0:36 offset1:44
	s_waitcnt lgkmcnt(5)
	v_mfma_f32_16x16x32_bf16 v[110:113], v[228:231], v[118:121], v[110:113]
	ds_read2st64_b64 v[224:227], v180 offset0:52 offset1:60
	s_waitcnt lgkmcnt(5)
	v_mfma_f32_16x16x32_bf16 v[110:113], v[232:235], v[94:97], v[110:113]
	ds_read_b128 v[228:231], v181 offset:34816
	v_mul_f32_e32 v240, v107, v107
	v_mul_f32_e32 v241, v109, v109
	v_fmac_f32_e32 v240, v106, v106
	v_fmac_f32_e32 v241, v108, v108
	v_add_f32_e32 v240, v240, v241
	v_add_f32_e32 v242, v242, v240
	s_waitcnt lgkmcnt(5)
	v_mfma_f32_16x16x32_bf16 v[110:113], v[208:211], v[90:93], v[110:113]
	ds_read_b128 v[232:235], v181 offset:34880
	s_waitcnt lgkmcnt(5)
	v_mfma_f32_16x16x32_bf16 v[110:113], v[212:215], v[86:89], v[110:113]
	ds_read_b128 v[208:211], v181 offset:53248
	s_waitcnt lgkmcnt(5)
	v_mfma_f32_16x16x32_bf16 v[110:113], v[216:219], v[82:85], v[110:113]
	ds_read_b128 v[212:215], v181 offset:53312
	s_waitcnt lgkmcnt(5)
	v_mfma_f32_16x16x32_bf16 v[122:125], v[220:223], v[114:117], 0
	ds_read2st64_b64 v[216:219], v182 offset0:36 offset1:44
	s_waitcnt lgkmcnt(5)
	v_mfma_f32_16x16x32_bf16 v[122:125], v[224:227], v[118:121], v[122:125]
	ds_read2st64_b64 v[220:223], v182 offset0:52 offset1:60
	s_waitcnt lgkmcnt(5)
	v_mfma_f32_16x16x32_bf16 v[122:125], v[228:231], v[94:97], v[122:125]
	ds_read_b128 v[224:227], v181 offset:37120
	v_mul_f32_e32 v240, v111, v111
	v_mul_f32_e32 v241, v113, v113
	v_fmac_f32_e32 v240, v110, v110
	v_fmac_f32_e32 v241, v112, v112
	v_add_f32_e32 v240, v240, v241
	v_add_f32_e32 v242, v242, v240
	s_waitcnt lgkmcnt(5)
	v_mfma_f32_16x16x32_bf16 v[122:125], v[232:235], v[90:93], v[122:125]
	ds_read_b128 v[228:231], v181 offset:37184
	s_waitcnt lgkmcnt(5)
	v_mfma_f32_16x16x32_bf16 v[122:125], v[208:211], v[86:89], v[122:125]
	ds_read_b128 v[232:235], v181 offset:55552
	s_waitcnt lgkmcnt(5)
	v_mfma_f32_16x16x32_bf16 v[122:125], v[212:215], v[82:85], v[122:125]
	ds_read_b128 v[208:211], v181 offset:55616
	s_waitcnt lgkmcnt(5)
	v_mfma_f32_16x16x32_bf16 v[126:129], v[216:219], v[114:117], 0
	ds_read2st64_b64 v[212:215], v183 offset0:36 offset1:44
	s_waitcnt lgkmcnt(5)
	v_mfma_f32_16x16x32_bf16 v[126:129], v[220:223], v[118:121], v[126:129]
	ds_read2st64_b64 v[216:219], v183 offset0:52 offset1:60
	s_waitcnt lgkmcnt(5)
	v_mfma_f32_16x16x32_bf16 v[126:129], v[224:227], v[94:97], v[126:129]
	ds_read_b128 v[220:223], v181 offset:39424
	v_mul_f32_e32 v240, v123, v123
	v_mul_f32_e32 v241, v125, v125
	v_fmac_f32_e32 v240, v122, v122
	v_fmac_f32_e32 v241, v124, v124
	v_add_f32_e32 v240, v240, v241
	v_add_f32_e32 v242, v242, v240
	s_waitcnt lgkmcnt(5)
	v_mfma_f32_16x16x32_bf16 v[126:129], v[228:231], v[90:93], v[126:129]
	ds_read_b128 v[224:227], v181 offset:39488
	s_waitcnt lgkmcnt(5)
	v_mfma_f32_16x16x32_bf16 v[126:129], v[232:235], v[86:89], v[126:129]
	ds_read_b128 v[228:231], v181 offset:57856
	s_waitcnt lgkmcnt(5)
	v_mfma_f32_16x16x32_bf16 v[126:129], v[208:211], v[82:85], v[126:129]
	ds_read_b128 v[232:235], v181 offset:57920
	s_waitcnt lgkmcnt(5)
	v_mfma_f32_16x16x32_bf16 v[130:133], v[212:215], v[114:117], 0
	ds_read2st64_b64 v[208:211], v184 offset0:36 offset1:44
	s_waitcnt lgkmcnt(5)
	v_mfma_f32_16x16x32_bf16 v[130:133], v[216:219], v[118:121], v[130:133]
	ds_read2st64_b64 v[212:215], v184 offset0:52 offset1:60
	s_waitcnt lgkmcnt(5)
	v_mfma_f32_16x16x32_bf16 v[130:133], v[220:223], v[94:97], v[130:133]
	ds_read_b128 v[216:219], v185 offset:34816
	v_mul_f32_e32 v240, v127, v127
	v_mul_f32_e32 v241, v129, v129
	v_fmac_f32_e32 v240, v126, v126
	v_fmac_f32_e32 v241, v128, v128
	v_add_f32_e32 v240, v240, v241
	v_add_f32_e32 v242, v242, v240
	s_waitcnt lgkmcnt(5)
	v_mfma_f32_16x16x32_bf16 v[130:133], v[224:227], v[90:93], v[130:133]
	ds_read_b128 v[220:223], v185 offset:34880
	s_waitcnt lgkmcnt(5)
	v_mfma_f32_16x16x32_bf16 v[130:133], v[228:231], v[86:89], v[130:133]
	ds_read_b128 v[224:227], v185 offset:53248
	s_waitcnt lgkmcnt(5)
	v_mfma_f32_16x16x32_bf16 v[130:133], v[232:235], v[82:85], v[130:133]
	ds_read_b128 v[228:231], v185 offset:53312
	s_waitcnt lgkmcnt(5)
	v_mfma_f32_16x16x32_bf16 v[236:239], v[208:211], v[114:117], 0
	s_waitcnt lgkmcnt(4)
	v_mfma_f32_16x16x32_bf16 v[236:239], v[212:215], v[118:121], v[236:239]
	s_waitcnt lgkmcnt(3)
	v_mfma_f32_16x16x32_bf16 v[236:239], v[216:219], v[94:97], v[236:239]
	v_mul_f32_e32 v240, v131, v131
	v_mul_f32_e32 v241, v133, v133
	v_fmac_f32_e32 v240, v130, v130
	v_fmac_f32_e32 v241, v132, v132
	v_add_f32_e32 v240, v240, v241
	v_add_f32_e32 v242, v242, v240
	s_waitcnt lgkmcnt(2)
; DI unsigned pk2(float lo, float hi) { return pg8::cvt_pk_bf16(lo, hi); }
; DI float bflo(unsigned w) { return __uint_as_float(w << 16); }
; DI float bfhi(unsigned w) { return __uint_as_float(w & 0xffff0000u); }
; DI float silu_f(float x) { return x * __builtin_amdgcn_rcpf(1.0f + __expf(-x)); }
; #define INP(i) ((const float*)karg(8 * (i)))
; DI void go_compute(int l, const unsigned char* base, const bf16x8 (&qq)[4], int item, int tb, int lane) {
;     ...
;         o[eb] = acc; ss += (acc[0] * acc[0] + acc[1] * acc[1]) + (acc[2] * acc[2] + acc[3] * acc[3]);
;     }
;     ss += __shfl_xor(ss, 16); ss += __shfl_xor(ss, 32);
;     const float rstd = rsqrtf(ss * (1.0f / 128.0f) + EPS);
;     const float* gain = INP(13) + l * 128 + 4 * g;
;     const size_t tok = tok0 + 16 * tb + c;
; #pragma unroll
;     for (int eb = 0; eb < 8; ++eb) {
;         const f32x4 gn = *(const f32x4*)(gain + 16 * eb);
;         const u32x2 gr = *(const u32x2*)(GR + tok * 512 + h * 128 + 16 * eb + 4 * g);
;         const float r0 = bflo(gr.x), r1 = bfhi(gr.x), r2 = bflo(gr.y), r3 = bfhi(gr.y);
;         u32x2 w; w.x = pk2(o[eb][0] * rstd * gn[0] * silu_f(r0), o[eb][1] * rstd * gn[1] * silu_f(r1)); w.y = pk2(o[eb][2] * rstd * gn[2] * silu_f(r2), o[eb][3] * rstd * gn[3] * silu_f(r3));
;         *(u32x2*)(MIX + tok * 1024 + 512 + h * 128 + 16 * eb + 4 * g) = w;
;     }
	v_mfma_f32_16x16x32_bf16 v[236:239], v[220:223], v[90:93], v[236:239]
	s_waitcnt lgkmcnt(1)
	v_mfma_f32_16x16x32_bf16 v[236:239], v[224:227], v[86:89], v[236:239]
	s_waitcnt lgkmcnt(0)
	v_mfma_f32_16x16x32_bf16 v[82:85], v[228:231], v[82:85], v[236:239]
	s_nop 7
	v_mul_f32_e32 v240, v83, v83
	v_mul_f32_e32 v241, v85, v85
	v_fmac_f32_e32 v240, v82, v82
	v_fmac_f32_e32 v241, v84, v84
	v_add_f32_e32 v240, v240, v241
	v_add_f32_e32 v242, v242, v240
	s_ashr_i32 s15, s12, 31
	s_add_u32 s14, s0, s12
	s_addc_u32 s15, s1, s15
	s_load_dwordx2 s[14:15], s[14:15], 0x0
	v_lshlrev_b32_e32 v91, 2, v152
	v_mov_b32_e32 v116, v242
	s_waitcnt lgkmcnt(0)
	s_add_u32 s14, s14, s2
	s_addc_u32 s15, s15, s3
	global_load_dwordx4 v[208:211], v91, s[14:15]
	global_load_dwordx4 v[212:215], v91, s[14:15] offset:64
	global_load_dwordx4 v[216:219], v91, s[14:15] offset:128
	global_load_dwordx4 v[220:223], v91, s[14:15] offset:192
	global_load_dwordx4 v[224:227], v91, s[14:15] offset:256
	global_load_dwordx4 v[228:231], v91, s[14:15] offset:320
	global_load_dwordx4 v[232:235], v91, s[14:15] offset:384
	global_load_dwordx4 v[236:239], v91, s[14:15] offset:448
	v_mov_b32_e32 v87, s13
	v_or_b32_e32 v86, s8, v148
	v_lshlrev_b64 v[88:89], 10, v[86:87]
	s_and_b32 s8, s29, 0x180
	v_lshl_add_u64 v[88:89], s[40:41], 0, v[88:89]
	s_lshl_b32 s8, s8, 1
	v_lshlrev_b64 v[86:87], 11, v[86:87]
	v_lshl_add_u64 v[88:89], v[88:89], 0, s[8:9]
	v_lshlrev_b32_e32 v0, 1, v152
	v_lshl_add_u64 v[86:87], s[40:41], 0, v[86:87]
	v_lshl_add_u64 v[96:97], v[88:89], 0, v[0:1]
	v_lshl_add_u64 v[86:87], v[86:87], 0, s[8:9]
	s_mov_b64 s[12:13], 0x11600000
	s_mov_b32 s8, 0x11600000
	v_lshl_add_u64 v[94:95], v[96:97], 0, s[12:13]
	v_add_co_u32_e32 v96, vcc, s8, v96
	v_lshl_add_u64 v[114:115], v[86:87], 0, v[0:1]
	s_nop 0
	v_addc_co_u32_e32 v97, vcc, 0, v97, vcc
	global_load_dwordx2 v[240:241], v[94:95], off
	global_load_dwordx2 v[242:243], v[94:95], off offset:32
	v_and_b32_e32 v87, 64, v194
	v_xor_b32_e32 v86, 16, v194
	v_add_u32_e32 v87, 64, v87
	v_cmp_lt_i32_e32 vcc, v86, v87
	s_nop 1
	v_cndmask_b32_e32 v86, v194, v86, vcc
	v_lshlrev_b32_e32 v86, 2, v86
	ds_bpermute_b32 v86, v86, v116
	s_waitcnt lgkmcnt(0)
	v_add_f32_e32 v116, v116, v86
	v_xor_b32_e32 v86, 32, v194
	v_cmp_lt_i32_e32 vcc, v86, v87
	s_nop 1
	v_cndmask_b32_e32 v86, v194, v86, vcc
	v_lshlrev_b32_e32 v86, 2, v86
	ds_bpermute_b32 v86, v86, v116
	s_waitcnt lgkmcnt(0)
	v_add_f32_e32 v116, v116, v86
	v_fmamk_f32 v116, v116, 0x3c000000, v164
	v_cmp_gt_f32_e32 vcc, s25, v116
	v_mul_f32_e32 v86, 0x4b800000, v116
	s_nop 0
	v_cndmask_b32_e32 v116, v116, v86, vcc
	v_rsq_f32_e32 v116, v116
	s_nop 0
	v_mul_f32_e32 v86, 0x45800000, v116
	v_cndmask_b32_e32 v90, v116, v86, vcc
	v_pk_mul_f32 v[98:99], v[98:99], v[90:91] op_sel_hi:[1,0]
	v_pk_mul_f32 v[100:101], v[100:101], v[90:91] op_sel_hi:[1,0]
	s_mov_b32 s8, 0x1b600000
	v_pk_mul_f32 v[102:103], v[102:103], v[90:91] op_sel_hi:[1,0]
	s_mov_b64 s[12:13], 0x1b600400
	v_lshl_add_u64 v[92:93], v[114:115], 0, s[12:13]
	v_pk_mul_f32 v[82:83], v[82:83], v[90:91] op_sel_hi:[1,0]
	v_pk_mul_f32 v[84:85], v[84:85], v[90:91] op_sel_hi:[1,0]
	s_waitcnt vmcnt(1)
	s_nop 1
	v_mov_b32_e32 v86, v208
	v_mov_b32_e32 v87, v209
	v_mov_b32_e32 v88, v210
	v_mov_b32_e32 v89, v211
	v_mov_b32_e32 v96, v240
	v_mov_b32_e32 v97, v241
	global_load_dwordx2 v[240:241], v[94:95], off offset:64
	v_lshlrev_b32_e32 v116, 16, v96
	v_mul_f32_e32 v0, 0xbfb8aa3b, v116
	v_exp_f32_e32 v0, v0
	v_and_b32_e32 v117, 0xffff0000, v96
	v_lshlrev_b32_e32 v96, 16, v97
	v_pk_mul_f32 v[86:87], v[86:87], v[98:99]
	v_add_f32_e32 v0, 1.0, v0
	v_rcp_f32_e32 v118, v0
	v_mul_f32_e32 v0, 0xbfb8aa3b, v117
	v_exp_f32_e32 v0, v0
	v_and_b32_e32 v97, 0xffff0000, v97
	v_pk_mul_f32 v[88:89], v[88:89], v[100:101]
	v_add_f32_e32 v0, 1.0, v0
	v_rcp_f32_e32 v119, v0
	v_mul_f32_e32 v0, 0xbfb8aa3b, v96
	v_exp_f32_e32 v0, v0
	v_pk_mul_f32 v[98:99], v[118:119], v[116:117]
	s_nop 0
	v_pk_mul_f32 v[86:87], v[86:87], v[98:99]
	v_add_f32_e32 v0, 1.0, v0
	v_rcp_f32_e32 v98, v0
	v_mul_f32_e32 v0, 0xbfb8aa3b, v97
	v_exp_f32_e32 v0, v0
	v_cvt_pk_bf16_f32 v86, v86, v87
	v_add_f32_e32 v0, 1.0, v0
	v_rcp_f32_e32 v99, v0
	s_nop 0
	v_pk_mul_f32 v[96:97], v[98:99], v[96:97]
	s_nop 0
	v_pk_mul_f32 v[88:89], v[88:89], v[96:97]
	s_nop 0
	v_cvt_pk_bf16_f32 v87, v88, v89
	v_add_co_u32_e32 v88, vcc, s8, v114
	v_readlane_b32 s8, v244, 5
	s_nop 0
	v_addc_co_u32_e32 v89, vcc, 0, v115, vcc
	global_store_dwordx2 v[88:89], v[86:87], off offset:1024
	s_nop 0
	s_add_i32 s29, s29, s8
	v_readlane_b32 s8, v244, 8
	s_add_i32 s30, s30, s8
	v_readlane_b32 s8, v244, 10
	s_add_i32 s31, s31, s8
	s_andn2_b64 vcc, exec, s[38:39]
	s_waitcnt vmcnt(2)
	s_nop 1
	v_mov_b32_e32 v86, v212
	v_mov_b32_e32 v87, v213
	v_mov_b32_e32 v88, v214
	v_mov_b32_e32 v89, v215
	v_mov_b32_e32 v96, v242
	v_mov_b32_e32 v97, v243
	global_load_dwordx2 v[242:243], v[94:95], off offset:96
	v_pk_mul_f32 v[86:87], v[86:87], v[102:103]
	v_lshlrev_b32_e32 v98, 16, v96
	v_mul_f32_e32 v0, 0xbfb8aa3b, v98
	v_exp_f32_e32 v0, v0
	v_and_b32_e32 v99, 0xffff0000, v96
	v_lshlrev_b32_e32 v96, 16, v97
	v_and_b32_e32 v97, 0xffff0000, v97
	v_add_f32_e32 v0, 1.0, v0
	v_rcp_f32_e32 v100, v0
	v_mul_f32_e32 v0, 0xbfb8aa3b, v99
	v_exp_f32_e32 v0, v0
	v_pk_mul_f32 v[102:103], v[106:107], v[90:91] op_sel_hi:[1,0]
	v_add_f32_e32 v0, 1.0, v0
	v_rcp_f32_e32 v101, v0
	v_mul_f32_e32 v0, 0xbfb8aa3b, v96
	v_exp_f32_e32 v0, v0
	v_pk_mul_f32 v[98:99], v[100:101], v[98:99]
	s_nop 0
	v_pk_mul_f32 v[86:87], v[86:87], v[98:99]
	v_add_f32_e32 v0, 1.0, v0
	v_rcp_f32_e32 v98, v0
	v_mul_f32_e32 v0, 0xbfb8aa3b, v97
	v_exp_f32_e32 v0, v0
	v_pk_mul_f32 v[100:101], v[104:105], v[90:91] op_sel_hi:[1,0]
	v_cvt_pk_bf16_f32 v86, v86, v87
	v_pk_mul_f32 v[88:89], v[88:89], v[100:101]
	v_add_f32_e32 v0, 1.0, v0
	v_rcp_f32_e32 v99, v0
	s_nop 0
	v_pk_mul_f32 v[96:97], v[98:99], v[96:97]
	s_nop 0
	v_pk_mul_f32 v[88:89], v[88:89], v[96:97]
	s_nop 0
	v_cvt_pk_bf16_f32 v87, v88, v89
	global_store_dwordx2 v[92:93], v[86:87], off offset:32
	s_nop 0
	s_waitcnt vmcnt(3)
; DI unsigned pk2(float lo, float hi) { return pg8::cvt_pk_bf16(lo, hi); }
; DI float bflo(unsigned w) { return __uint_as_float(w << 16); }
; DI float bfhi(unsigned w) { return __uint_as_float(w & 0xffff0000u); }
; DI float silu_f(float x) { return x * __builtin_amdgcn_rcpf(1.0f + __expf(-x)); }
; DI void go_compute(int l, const unsigned char* base, const bf16x8 (&qq)[4], int item, int tb, int lane) {
;     ...
; #pragma unroll
;     for (int eb = 0; eb < 8; ++eb) {
;         const f32x4 gn = *(const f32x4*)(gain + 16 * eb);
;         const u32x2 gr = *(const u32x2*)(GR + tok * 512 + h * 128 + 16 * eb + 4 * g);
;         const float r0 = bflo(gr.x), r1 = bfhi(gr.x), r2 = bflo(gr.y), r3 = bfhi(gr.y);
;         u32x2 w; w.x = pk2(o[eb][0] * rstd * gn[0] * silu_f(r0), o[eb][1] * rstd * gn[1] * silu_f(r1)); w.y = pk2(o[eb][2] * rstd * gn[2] * silu_f(r2), o[eb][3] * rstd * gn[3] * silu_f(r3));
;         *(u32x2*)(MIX + tok * 1024 + 512 + h * 128 + 16 * eb + 4 * g) = w;
;     }
	s_nop 1
	v_mov_b32_e32 v86, v216
	v_mov_b32_e32 v87, v217
	v_mov_b32_e32 v88, v218
	v_mov_b32_e32 v89, v219
	v_mov_b32_e32 v96, v240
	v_mov_b32_e32 v97, v241
	global_load_dwordx2 v[240:241], v[94:95], off offset:128
	v_pk_mul_f32 v[86:87], v[86:87], v[102:103]
	v_lshlrev_b32_e32 v98, 16, v96
	v_mul_f32_e32 v0, 0xbfb8aa3b, v98
	v_exp_f32_e32 v0, v0
	v_and_b32_e32 v99, 0xffff0000, v96
	v_lshlrev_b32_e32 v96, 16, v97
	v_and_b32_e32 v97, 0xffff0000, v97
	v_add_f32_e32 v0, 1.0, v0
	v_rcp_f32_e32 v100, v0
	v_mul_f32_e32 v0, 0xbfb8aa3b, v99
	v_exp_f32_e32 v0, v0
	v_pk_mul_f32 v[102:103], v[110:111], v[90:91] op_sel_hi:[1,0]
	v_add_f32_e32 v0, 1.0, v0
	v_rcp_f32_e32 v101, v0
	v_mul_f32_e32 v0, 0xbfb8aa3b, v96
	v_exp_f32_e32 v0, v0
	v_pk_mul_f32 v[98:99], v[100:101], v[98:99]
	s_nop 0
	v_pk_mul_f32 v[86:87], v[86:87], v[98:99]
	v_add_f32_e32 v0, 1.0, v0
	v_rcp_f32_e32 v98, v0
	v_mul_f32_e32 v0, 0xbfb8aa3b, v97
	v_exp_f32_e32 v0, v0
	v_pk_mul_f32 v[100:101], v[108:109], v[90:91] op_sel_hi:[1,0]
	v_cvt_pk_bf16_f32 v86, v86, v87
	v_pk_mul_f32 v[88:89], v[88:89], v[100:101]
	v_add_f32_e32 v0, 1.0, v0
	v_rcp_f32_e32 v99, v0
	s_nop 0
	v_pk_mul_f32 v[96:97], v[98:99], v[96:97]
	s_nop 0
	v_pk_mul_f32 v[88:89], v[88:89], v[96:97]
	s_nop 0
	v_cvt_pk_bf16_f32 v87, v88, v89
	global_store_dwordx2 v[92:93], v[86:87], off offset:64
	s_nop 0
	s_waitcnt vmcnt(3)
	s_nop 1
	v_mov_b32_e32 v86, v220
	v_mov_b32_e32 v87, v221
	v_mov_b32_e32 v88, v222
	v_mov_b32_e32 v89, v223
	v_mov_b32_e32 v96, v242
	v_mov_b32_e32 v97, v243
	global_load_dwordx2 v[242:243], v[94:95], off offset:160
	v_pk_mul_f32 v[86:87], v[102:103], v[86:87]
	v_lshlrev_b32_e32 v98, 16, v96
	v_mul_f32_e32 v0, 0xbfb8aa3b, v98
	v_exp_f32_e32 v0, v0
	v_and_b32_e32 v99, 0xffff0000, v96
	v_lshlrev_b32_e32 v96, 16, v97
	v_and_b32_e32 v97, 0xffff0000, v97
	v_add_f32_e32 v0, 1.0, v0
	v_rcp_f32_e32 v100, v0
	v_mul_f32_e32 v0, 0xbfb8aa3b, v99
	v_exp_f32_e32 v0, v0
	v_pk_mul_f32 v[102:103], v[122:123], v[90:91] op_sel_hi:[1,0]
	v_add_f32_e32 v0, 1.0, v0
	v_rcp_f32_e32 v101, v0
	v_mul_f32_e32 v0, 0xbfb8aa3b, v96
	v_exp_f32_e32 v0, v0
	v_pk_mul_f32 v[98:99], v[100:101], v[98:99]
	s_nop 0
	v_pk_mul_f32 v[86:87], v[86:87], v[98:99]
	v_add_f32_e32 v0, 1.0, v0
	v_rcp_f32_e32 v98, v0
	v_mul_f32_e32 v0, 0xbfb8aa3b, v97
	v_exp_f32_e32 v0, v0
	v_pk_mul_f32 v[100:101], v[112:113], v[90:91] op_sel_hi:[1,0]
	v_cvt_pk_bf16_f32 v86, v86, v87
	v_pk_mul_f32 v[88:89], v[100:101], v[88:89]
	v_add_f32_e32 v0, 1.0, v0
	v_rcp_f32_e32 v99, v0
	s_nop 0
	v_pk_mul_f32 v[96:97], v[98:99], v[96:97]
	s_nop 0
	v_pk_mul_f32 v[88:89], v[88:89], v[96:97]
	s_nop 0
	v_cvt_pk_bf16_f32 v87, v88, v89
	global_store_dwordx2 v[92:93], v[86:87], off offset:96
	s_nop 0
	s_waitcnt vmcnt(3)
	s_nop 1
	v_mov_b32_e32 v86, v224
	v_mov_b32_e32 v87, v225
	v_mov_b32_e32 v88, v226
	v_mov_b32_e32 v89, v227
	v_mov_b32_e32 v96, v240
	v_mov_b32_e32 v97, v241
	global_load_dwordx2 v[240:241], v[94:95], off offset:192
	v_pk_mul_f32 v[86:87], v[102:103], v[86:87]
	v_lshlrev_b32_e32 v98, 16, v96
	v_mul_f32_e32 v0, 0xbfb8aa3b, v98
	v_exp_f32_e32 v0, v0
	v_and_b32_e32 v99, 0xffff0000, v96
	v_lshlrev_b32_e32 v96, 16, v97
	v_and_b32_e32 v97, 0xffff0000, v97
	v_add_f32_e32 v0, 1.0, v0
	v_rcp_f32_e32 v100, v0
	v_mul_f32_e32 v0, 0xbfb8aa3b, v99
	v_exp_f32_e32 v0, v0
	v_pk_mul_f32 v[102:103], v[126:127], v[90:91] op_sel_hi:[1,0]
	v_add_f32_e32 v0, 1.0, v0
	v_rcp_f32_e32 v101, v0
	v_mul_f32_e32 v0, 0xbfb8aa3b, v96
	v_exp_f32_e32 v0, v0
	v_pk_mul_f32 v[98:99], v[100:101], v[98:99]
	s_nop 0
	v_pk_mul_f32 v[86:87], v[86:87], v[98:99]
	v_add_f32_e32 v0, 1.0, v0
	v_rcp_f32_e32 v98, v0
	v_mul_f32_e32 v0, 0xbfb8aa3b, v97
	v_exp_f32_e32 v0, v0
	v_pk_mul_f32 v[100:101], v[124:125], v[90:91] op_sel_hi:[1,0]
	v_cvt_pk_bf16_f32 v86, v86, v87
	v_pk_mul_f32 v[88:89], v[100:101], v[88:89]
	v_add_f32_e32 v0, 1.0, v0
	v_rcp_f32_e32 v99, v0
	s_nop 0
	v_pk_mul_f32 v[96:97], v[98:99], v[96:97]
	s_nop 0
	v_pk_mul_f32 v[88:89], v[88:89], v[96:97]
	s_nop 0
	v_cvt_pk_bf16_f32 v87, v88, v89
	global_store_dwordx2 v[92:93], v[86:87], off offset:128
	s_nop 0
	s_waitcnt vmcnt(3)
; DI unsigned pk2(float lo, float hi) { return pg8::cvt_pk_bf16(lo, hi); }
; DI float bflo(unsigned w) { return __uint_as_float(w << 16); }
; DI float bfhi(unsigned w) { return __uint_as_float(w & 0xffff0000u); }
; DI float silu_f(float x) { return x * __builtin_amdgcn_rcpf(1.0f + __expf(-x)); }
; #define SCHED_FENCE() __builtin_amdgcn_sched_barrier(0)
; DI void go_compute(int l, const unsigned char* base, const bf16x8 (&qq)[4], int item, int tb, int lane) {
;     ...
; #pragma unroll
;     for (int eb = 0; eb < 8; ++eb) {
;         const f32x4 gn = *(const f32x4*)(gain + 16 * eb);
;         const u32x2 gr = *(const u32x2*)(GR + tok * 512 + h * 128 + 16 * eb + 4 * g);
;         const float r0 = bflo(gr.x), r1 = bfhi(gr.x), r2 = bflo(gr.y), r3 = bfhi(gr.y);
;         u32x2 w; w.x = pk2(o[eb][0] * rstd * gn[0] * silu_f(r0), o[eb][1] * rstd * gn[1] * silu_f(r1)); w.y = pk2(o[eb][2] * rstd * gn[2] * silu_f(r2), o[eb][3] * rstd * gn[3] * silu_f(r3));
;         *(u32x2*)(MIX + tok * 1024 + 512 + h * 128 + 16 * eb + 4 * g) = w;
;     }
; DI void gla_out_phase(int l, unsigned char* ldsb, int tid, int wave, int lane, bool xl, int xq, int k0, int kend, int kstep) {
;     ...
;         bf16x8 qq[4] = {st.q[0], st.q[1], st.q[2], st.q[3]};
;         __syncthreads();
;         if (k + kstep < kend) go_gload(st, go_item(xl, xq, k + kstep, half), t256, tb, lane);
;         SCHED_FENCE();
;         go_compute(l, base, qq, go_item(xl, xq, k, half), tb, lane);
;         __syncthreads();
	s_nop 1
	v_mov_b32_e32 v86, v228
	v_mov_b32_e32 v87, v229
	v_mov_b32_e32 v88, v230
	v_mov_b32_e32 v89, v231
	v_mov_b32_e32 v96, v242
	v_mov_b32_e32 v97, v243
	global_load_dwordx2 v[242:243], v[94:95], off offset:224
	v_pk_mul_f32 v[86:87], v[102:103], v[86:87]
	v_lshlrev_b32_e32 v98, 16, v96
	v_mul_f32_e32 v0, 0xbfb8aa3b, v98
	v_exp_f32_e32 v0, v0
	v_and_b32_e32 v99, 0xffff0000, v96
	v_lshlrev_b32_e32 v96, 16, v97
	v_and_b32_e32 v97, 0xffff0000, v97
	v_add_f32_e32 v0, 1.0, v0
	v_rcp_f32_e32 v100, v0
	v_mul_f32_e32 v0, 0xbfb8aa3b, v99
	v_exp_f32_e32 v0, v0
	v_pk_mul_f32 v[102:103], v[130:131], v[90:91] op_sel_hi:[1,0]
	v_add_f32_e32 v0, 1.0, v0
	v_rcp_f32_e32 v101, v0
	v_mul_f32_e32 v0, 0xbfb8aa3b, v96
	v_exp_f32_e32 v0, v0
	v_pk_mul_f32 v[98:99], v[100:101], v[98:99]
	s_nop 0
	v_pk_mul_f32 v[86:87], v[86:87], v[98:99]
	v_add_f32_e32 v0, 1.0, v0
	v_rcp_f32_e32 v98, v0
	v_mul_f32_e32 v0, 0xbfb8aa3b, v97
	v_exp_f32_e32 v0, v0
	v_pk_mul_f32 v[100:101], v[128:129], v[90:91] op_sel_hi:[1,0]
	v_cvt_pk_bf16_f32 v86, v86, v87
	v_pk_mul_f32 v[88:89], v[100:101], v[88:89]
	v_add_f32_e32 v0, 1.0, v0
	v_rcp_f32_e32 v99, v0
	s_nop 0
	v_pk_mul_f32 v[96:97], v[98:99], v[96:97]
	s_nop 0
	v_pk_mul_f32 v[88:89], v[88:89], v[96:97]
	s_nop 0
	v_cvt_pk_bf16_f32 v87, v88, v89
	global_store_dwordx2 v[92:93], v[86:87], off offset:160
	s_nop 0
	s_waitcnt vmcnt(3)
	s_nop 1
	v_mov_b32_e32 v86, v232
	v_mov_b32_e32 v87, v233
	v_mov_b32_e32 v88, v234
	v_mov_b32_e32 v89, v235
	v_mov_b32_e32 v96, v240
	v_mov_b32_e32 v97, v241
	v_pk_mul_f32 v[86:87], v[102:103], v[86:87]
	v_lshlrev_b32_e32 v98, 16, v96
	v_mul_f32_e32 v0, 0xbfb8aa3b, v98
	v_exp_f32_e32 v0, v0
	v_and_b32_e32 v99, 0xffff0000, v96
	v_lshlrev_b32_e32 v96, 16, v97
	v_and_b32_e32 v97, 0xffff0000, v97
	v_add_f32_e32 v0, 1.0, v0
	v_rcp_f32_e32 v100, v0
	v_mul_f32_e32 v0, 0xbfb8aa3b, v99
	v_exp_f32_e32 v0, v0
	s_nop 0
	v_add_f32_e32 v0, 1.0, v0
	v_rcp_f32_e32 v101, v0
	v_mul_f32_e32 v0, 0xbfb8aa3b, v96
	v_exp_f32_e32 v0, v0
	v_pk_mul_f32 v[98:99], v[100:101], v[98:99]
	s_nop 0
	v_pk_mul_f32 v[86:87], v[86:87], v[98:99]
	v_add_f32_e32 v0, 1.0, v0
	v_rcp_f32_e32 v98, v0
	v_mul_f32_e32 v0, 0xbfb8aa3b, v97
	v_exp_f32_e32 v0, v0
	v_pk_mul_f32 v[100:101], v[132:133], v[90:91] op_sel_hi:[1,0]
	v_cvt_pk_bf16_f32 v86, v86, v87
	v_pk_mul_f32 v[88:89], v[100:101], v[88:89]
	v_add_f32_e32 v0, 1.0, v0
	v_rcp_f32_e32 v99, v0
	s_nop 0
	v_pk_mul_f32 v[96:97], v[98:99], v[96:97]
	s_nop 0
	v_pk_mul_f32 v[88:89], v[88:89], v[96:97]
	s_nop 0
	v_cvt_pk_bf16_f32 v87, v88, v89
	global_store_dwordx2 v[92:93], v[86:87], off offset:192
	s_nop 0
	s_waitcnt vmcnt(2)
	s_nop 1
	v_mov_b32_e32 v86, v236
	v_mov_b32_e32 v87, v237
	v_mov_b32_e32 v88, v238
	v_mov_b32_e32 v89, v239
	v_mov_b32_e32 v94, v242
	v_mov_b32_e32 v95, v243
	v_pk_mul_f32 v[82:83], v[82:83], v[86:87]
	v_lshlrev_b32_e32 v96, 16, v94
	v_mul_f32_e32 v0, 0xbfb8aa3b, v96
	v_exp_f32_e32 v0, v0
	v_and_b32_e32 v97, 0xffff0000, v94
	v_pk_mul_f32 v[84:85], v[84:85], v[88:89]
	v_add_f32_e32 v0, 1.0, v0
	v_rcp_f32_e32 v98, v0
	v_mul_f32_e32 v0, 0xbfb8aa3b, v97
	v_exp_f32_e32 v0, v0
	s_nop 0
	v_add_f32_e32 v0, 1.0, v0
	v_rcp_f32_e32 v99, v0
	s_nop 0
	v_pk_mul_f32 v[86:87], v[98:99], v[96:97]
	s_nop 0
	v_pk_mul_f32 v[82:83], v[82:83], v[86:87]
	v_lshlrev_b32_e32 v86, 16, v95
	v_mul_f32_e32 v0, 0xbfb8aa3b, v86
	v_exp_f32_e32 v0, v0
	v_and_b32_e32 v87, 0xffff0000, v95
	v_cvt_pk_bf16_f32 v82, v82, v83
	v_add_f32_e32 v0, 1.0, v0
	v_rcp_f32_e32 v94, v0
	v_mul_f32_e32 v0, 0xbfb8aa3b, v87
	v_exp_f32_e32 v0, v0
	s_nop 0
	v_add_f32_e32 v0, 1.0, v0
	v_rcp_f32_e32 v95, v0
	s_nop 0
	v_pk_mul_f32 v[86:87], v[94:95], v[86:87]
	s_nop 0
	v_pk_mul_f32 v[84:85], v[84:85], v[86:87]
	v_mov_b64_e32 v[88:89], v[76:77]
	v_cvt_pk_bf16_f32 v83, v84, v85
	global_store_dwordx2 v[92:93], v[82:83], off offset:224
	v_mov_b64_e32 v[84:85], v[80:81]
	v_mov_b64_e32 v[92:93], v[72:73]
	v_mov_b64_e32 v[96:97], v[68:69]
	v_mov_b64_e32 v[82:83], v[78:79]
	v_mov_b64_e32 v[86:87], v[74:75]
	v_mov_b64_e32 v[90:91], v[70:71]
	v_mov_b64_e32 v[94:95], v[66:67]
	s_barrier
	s_cbranch_vccz .LBB0_876
